# branch-merge phase: both epilogues rewritten: the 24 gate loads issued together, first product kept in registers across the second K loop (no f32 scratch round trip), one wait + math + 12 stores
# speedup vs baseline: 1.0139x; 1.0132x over previous
.LBB0_107:
	s_waitcnt vmcnt(5)
	s_barrier
	s_mul_i32 s43, s13, 0xc000
	v_add_u32_e32 v63, s43, v60
	v_add_u32_e32 v66, 0x2000, v63
	v_readfirstlane_b32 s43, v63
	v_lshl_add_u64 v[64:65], v[58:59], 0, s[16:17]
	s_mov_b32 m0, s43
	v_readfirstlane_b32 s43, v66
	v_add_u32_e32 v66, 0x4000, v63
	global_load_lds_dwordx4 v[64:65], off
	v_lshl_add_u64 v[64:65], v[56:57], 0, s[16:17]
	s_mov_b32 m0, s43
	v_readfirstlane_b32 s43, v66
	v_add_u32_e32 v66, 0x8000, v63
	global_load_lds_dwordx4 v[64:65], off
	v_lshl_add_u64 v[64:65], v[54:55], 0, s[16:17]
	s_mov_b32 m0, s43
	v_readfirstlane_b32 s43, v66
	v_add_u32_e32 v63, 0xa000, v63
	global_load_lds_dwordx4 v[64:65], off
	v_lshl_add_u64 v[64:65], v[52:53], 0, s[16:17]
	s_mov_b32 m0, s43
	v_readfirstlane_b32 s43, v63
	global_load_lds_dwordx4 v[64:65], off
	v_lshl_add_u64 v[64:65], v[50:51], 0, s[16:17]
	s_mov_b32 m0, s43
	s_mul_i32 s43, s19, 0xc000
	global_load_lds_dwordx4 v[64:65], off
	v_add_u32_e32 v63, s43, v62
	ds_read_b128 v[64:67], v63 offset:0
	ds_read_b128 v[68:71], v63 offset:2048
	ds_read_b128 v[72:75], v63 offset:4096
	v_add_u32_e32 v116, s43, v61
	ds_read_b128 v[76:79], v116 offset:0
	ds_read_b128 v[80:83], v116 offset:2048
	ds_read_b128 v[84:87], v116 offset:4096
	ds_read_b128 v[88:91], v116 offset:6144
	ds_read_b128 v[92:95], v63 offset:1024
	ds_read_b128 v[96:99], v63 offset:3072
	ds_read_b128 v[100:103], v63 offset:5120
	ds_read_b128 v[104:107], v116 offset:1024
	ds_read_b128 v[108:111], v116 offset:3072
	ds_read_b128 v[112:115], v116 offset:5120
	ds_read_b128 v[116:119], v116 offset:7168
	s_waitcnt lgkmcnt(7)
	s_nop 0
	v_mfma_f32_16x16x32_bf16 v[46:49], v[76:79], v[64:67], v[46:49]
	v_mfma_f32_16x16x32_bf16 v[42:45], v[80:83], v[64:67], v[42:45]
	v_mfma_f32_16x16x32_bf16 v[38:41], v[84:87], v[64:67], v[38:41]
	v_mfma_f32_16x16x32_bf16 v[34:37], v[88:91], v[64:67], v[34:37]
	v_mfma_f32_16x16x32_bf16 v[30:33], v[76:79], v[68:71], v[30:33]
	v_mfma_f32_16x16x32_bf16 v[26:29], v[80:83], v[68:71], v[26:29]
	v_mfma_f32_16x16x32_bf16 v[22:25], v[84:87], v[68:71], v[22:25]
	v_mfma_f32_16x16x32_bf16 v[18:21], v[88:91], v[68:71], v[18:21]
	v_mfma_f32_16x16x32_bf16 v[14:17], v[76:79], v[72:75], v[14:17]
	v_mfma_f32_16x16x32_bf16 v[10:13], v[80:83], v[72:75], v[10:13]
	v_mfma_f32_16x16x32_bf16 v[6:9], v[84:87], v[72:75], v[6:9]
	v_mfma_f32_16x16x32_bf16 v[2:5], v[88:91], v[72:75], v[2:5]
	s_waitcnt lgkmcnt(0)
	v_mfma_f32_16x16x32_bf16 v[46:49], v[104:107], v[92:95], v[46:49]
	v_mfma_f32_16x16x32_bf16 v[42:45], v[108:111], v[92:95], v[42:45]
	v_mfma_f32_16x16x32_bf16 v[38:41], v[112:115], v[92:95], v[38:41]
	v_mfma_f32_16x16x32_bf16 v[34:37], v[116:119], v[92:95], v[34:37]
	v_mfma_f32_16x16x32_bf16 v[30:33], v[104:107], v[96:99], v[30:33]
	v_mfma_f32_16x16x32_bf16 v[26:29], v[108:111], v[96:99], v[26:29]
	v_mfma_f32_16x16x32_bf16 v[22:25], v[112:115], v[96:99], v[22:25]
	v_mfma_f32_16x16x32_bf16 v[18:21], v[116:119], v[96:99], v[18:21]
	v_mfma_f32_16x16x32_bf16 v[14:17], v[104:107], v[100:103], v[14:17]
	v_mfma_f32_16x16x32_bf16 v[10:13], v[108:111], v[100:103], v[10:13]
	v_mfma_f32_16x16x32_bf16 v[6:9], v[112:115], v[100:103], v[6:9]
	v_mfma_f32_16x16x32_bf16 v[2:5], v[116:119], v[100:103], v[2:5]
	s_add_i32 s43, s19, 1
	s_cmp_lg_u32 s19, 2
	s_cselect_b32 s19, s43, 0
	s_add_i32 s43, s13, 1
	s_cmp_lg_u32 s13, 2
	s_cselect_b32 s13, s43, 0
	s_add_u32 s16, s16, 0x80
	s_addc_u32 s17, s17, 0
	s_cmpk_eq_i32 s16, 0x700
	s_cbranch_scc0 .LBB0_107
	s_waitcnt vmcnt(5)
	v_and_b32_e32 v63, 64, v0
	s_barrier
	v_add_u32_e32 v58, 0x18000, v62
	ds_read_b128 v[50:53], v58 offset:0
	ds_read_b128 v[54:57], v58 offset:2048
	ds_read_b128 v[64:67], v58 offset:4096
	v_add_u32_e32 v59, 0x18000, v61
	ds_read_b128 v[68:71], v59 offset:0
	ds_read_b128 v[72:75], v59 offset:2048
	ds_read_b128 v[76:79], v59 offset:4096
	ds_read_b128 v[80:83], v59 offset:6144
	ds_read_b128 v[84:87], v58 offset:1024
	ds_read_b128 v[88:91], v58 offset:3072
	ds_read_b128 v[92:95], v58 offset:5120
	ds_read_b128 v[96:99], v59 offset:1024
	ds_read_b128 v[100:103], v59 offset:3072
	ds_read_b128 v[104:107], v59 offset:5120
	ds_read_b128 v[108:111], v59 offset:7168
	s_waitcnt lgkmcnt(7)
	s_nop 0
	v_mfma_f32_16x16x32_bf16 v[46:49], v[68:71], v[50:53], v[46:49]
	v_mfma_f32_16x16x32_bf16 v[42:45], v[72:75], v[50:53], v[42:45]
	v_mfma_f32_16x16x32_bf16 v[38:41], v[76:79], v[50:53], v[38:41]
	v_mfma_f32_16x16x32_bf16 v[34:37], v[80:83], v[50:53], v[34:37]
	v_mfma_f32_16x16x32_bf16 v[30:33], v[68:71], v[54:57], v[30:33]
	v_mfma_f32_16x16x32_bf16 v[26:29], v[72:75], v[54:57], v[26:29]
	v_mfma_f32_16x16x32_bf16 v[22:25], v[76:79], v[54:57], v[22:25]
	v_mfma_f32_16x16x32_bf16 v[18:21], v[80:83], v[54:57], v[18:21]
	v_mfma_f32_16x16x32_bf16 v[14:17], v[68:71], v[64:67], v[14:17]
	v_mfma_f32_16x16x32_bf16 v[10:13], v[72:75], v[64:67], v[10:13]
	v_mfma_f32_16x16x32_bf16 v[6:9], v[76:79], v[64:67], v[6:9]
	v_mfma_f32_16x16x32_bf16 v[2:5], v[80:83], v[64:67], v[2:5]
	s_waitcnt lgkmcnt(0)
	v_mfma_f32_16x16x32_bf16 v[46:49], v[96:99], v[84:87], v[46:49]
	v_mfma_f32_16x16x32_bf16 v[42:45], v[100:103], v[84:87], v[42:45]
	v_mfma_f32_16x16x32_bf16 v[38:41], v[104:107], v[84:87], v[38:41]
	v_mfma_f32_16x16x32_bf16 v[34:37], v[108:111], v[84:87], v[34:37]
	v_mfma_f32_16x16x32_bf16 v[30:33], v[96:99], v[88:91], v[30:33]
	v_mfma_f32_16x16x32_bf16 v[26:29], v[100:103], v[88:91], v[26:29]
	v_mfma_f32_16x16x32_bf16 v[22:25], v[104:107], v[88:91], v[22:25]
	v_mfma_f32_16x16x32_bf16 v[18:21], v[108:111], v[88:91], v[18:21]
	v_mfma_f32_16x16x32_bf16 v[14:17], v[96:99], v[92:95], v[14:17]
	v_mfma_f32_16x16x32_bf16 v[10:13], v[100:103], v[92:95], v[10:13]
	v_mfma_f32_16x16x32_bf16 v[6:9], v[104:107], v[92:95], v[6:9]
	v_mfma_f32_16x16x32_bf16 v[2:5], v[108:111], v[92:95], v[2:5]
	s_waitcnt vmcnt(0)
	v_ashrrev_i32_e32 v108, 7, v0
	s_barrier
	ds_read_b128 v[50:53], v62 offset:0
	ds_read_b128 v[54:57], v62 offset:2048
	ds_read_b128 v[64:67], v62 offset:4096
	ds_read_b128 v[68:71], v61 offset:0
	ds_read_b128 v[72:75], v61 offset:2048
	ds_read_b128 v[76:79], v61 offset:4096
	ds_read_b128 v[80:83], v61 offset:6144
	ds_read_b128 v[84:87], v62 offset:1024
	ds_read_b128 v[88:91], v62 offset:3072
	ds_read_b128 v[92:95], v62 offset:5120
	ds_read_b128 v[96:99], v61 offset:1024
	ds_read_b128 v[100:103], v61 offset:3072
	ds_read_b128 v[104:107], v61 offset:5120
	ds_read_b128 v[58:61], v61 offset:7168
	s_waitcnt lgkmcnt(7)
	s_nop 0
	v_mfma_f32_16x16x32_bf16 v[46:49], v[68:71], v[50:53], v[46:49]
	v_mfma_f32_16x16x32_bf16 v[42:45], v[72:75], v[50:53], v[42:45]
	v_mfma_f32_16x16x32_bf16 v[38:41], v[76:79], v[50:53], v[38:41]
	v_mfma_f32_16x16x32_bf16 v[34:37], v[80:83], v[50:53], v[34:37]
	v_mfma_f32_16x16x32_bf16 v[30:33], v[68:71], v[54:57], v[30:33]
	v_mfma_f32_16x16x32_bf16 v[26:29], v[72:75], v[54:57], v[26:29]
	v_mfma_f32_16x16x32_bf16 v[22:25], v[76:79], v[54:57], v[22:25]
	v_mfma_f32_16x16x32_bf16 v[18:21], v[80:83], v[54:57], v[18:21]
	v_mfma_f32_16x16x32_bf16 v[14:17], v[68:71], v[64:67], v[14:17]
	v_mfma_f32_16x16x32_bf16 v[10:13], v[72:75], v[64:67], v[10:13]
	v_mfma_f32_16x16x32_bf16 v[6:9], v[76:79], v[64:67], v[6:9]
	v_mfma_f32_16x16x32_bf16 v[2:5], v[80:83], v[64:67], v[2:5]
	s_waitcnt lgkmcnt(0)
	v_mfma_f32_16x16x32_bf16 v[46:49], v[96:99], v[84:87], v[46:49]
	v_mfma_f32_16x16x32_bf16 v[42:45], v[100:103], v[84:87], v[42:45]
	v_mfma_f32_16x16x32_bf16 v[38:41], v[104:107], v[84:87], v[38:41]
	v_mfma_f32_16x16x32_bf16 v[34:37], v[58:61], v[84:87], v[34:37]
	v_mfma_f32_16x16x32_bf16 v[52:55], v[96:99], v[88:91], v[30:33]
	v_mfma_f32_16x16x32_bf16 v[26:29], v[100:103], v[88:91], v[26:29]
	v_mfma_f32_16x16x32_bf16 v[22:25], v[104:107], v[88:91], v[22:25]
	v_mfma_f32_16x16x32_bf16 v[18:21], v[58:61], v[88:91], v[18:21]
	v_mfma_f32_16x16x32_bf16 v[14:17], v[96:99], v[92:95], v[14:17]
	v_mfma_f32_16x16x32_bf16 v[10:13], v[100:103], v[92:95], v[10:13]
	v_mfma_f32_16x16x32_bf16 v[6:9], v[104:107], v[92:95], v[6:9]
	v_mfma_f32_16x16x32_bf16 v[2:5], v[58:61], v[92:95], v[2:5]
	s_nop 7
	s_nop 1
	v_readlane_b32 s16, v217, 26
	v_readlane_b32 s17, v217, 27
	s_and_b32 vcc_lo, s42, 31
	s_mul_i32 vcc_lo, vcc_lo, 192
	s_lshr_b32 vcc_hi, s42, 5
	s_lshl_b32 vcc_hi, vcc_hi, 8
	v_and_b32_e32 v93, 15, v142
	v_lshrrev_b32_e32 v94, 7, v142
	v_mad_u32_u24 v93, v94, 48, v93
	v_add_u32_e32 v93, vcc_lo, v93
	v_lshrrev_b32_e32 v94, 4, v142
	v_and_b32_e32 v94, 3, v94
	v_lshlrev_b32_e32 v94, 3, v94
	v_lshrrev_b32_e32 v95, 6, v142
	v_and_b32_e32 v95, 1, v95
	v_lshl_add_u32 v94, v95, 7, v94
	v_add_u32_e32 v94, vcc_hi, v94
	v_lshl_add_u32 v90, v93, 12, v94
	v_add_u32_e32 v91, 0x10000, v90
	v_add_u32_e32 v92, 0x10000, v91
	global_load_dwordx2 v[66:67], v90, s[16:17] offset:0
	global_load_dwordx2 v[68:69], v90, s[16:17] offset:32
	global_load_dwordx2 v[70:71], v90, s[16:17] offset:64
	global_load_dwordx2 v[72:73], v90, s[16:17] offset:96
	global_load_dwordx2 v[74:75], v91, s[16:17] offset:0
	global_load_dwordx2 v[76:77], v91, s[16:17] offset:32
	global_load_dwordx2 v[78:79], v91, s[16:17] offset:64
	global_load_dwordx2 v[80:81], v91, s[16:17] offset:96
	global_load_dwordx2 v[82:83], v92, s[16:17] offset:0
	global_load_dwordx2 v[84:85], v92, s[16:17] offset:32
	global_load_dwordx2 v[86:87], v92, s[16:17] offset:64
	global_load_dwordx2 v[88:89], v92, s[16:17] offset:96
	global_load_dwordx2 v[218:219], v90, s[16:17] offset:2048
	global_load_dwordx2 v[220:221], v90, s[16:17] offset:2080
	global_load_dwordx2 v[222:223], v90, s[16:17] offset:2112
	global_load_dwordx2 v[224:225], v90, s[16:17] offset:2144
	global_load_dwordx2 v[226:227], v91, s[16:17] offset:2048
	global_load_dwordx2 v[228:229], v91, s[16:17] offset:2080
	global_load_dwordx2 v[230:231], v91, s[16:17] offset:2112
	global_load_dwordx2 v[232:233], v91, s[16:17] offset:2144
	global_load_dwordx2 v[234:235], v92, s[16:17] offset:2048
	global_load_dwordx2 v[236:237], v92, s[16:17] offset:2080
	global_load_dwordx2 v[238:239], v92, s[16:17] offset:2112
	global_load_dwordx2 v[240:241], v92, s[16:17] offset:2144
	s_waitcnt vmcnt(12)
	v_lshlrev_b32_e32 v96, 16, v66
	v_and_b32_e32 v97, 0xffff0000, v66
	v_lshlrev_b32_e32 v98, 16, v67
	v_and_b32_e32 v99, 0xffff0000, v67
	v_pk_mul_f32 v[162:163], v[46:47], v[96:97]
	v_pk_mul_f32 v[164:165], v[48:49], v[98:99]
	v_lshlrev_b32_e32 v100, 16, v68
	v_and_b32_e32 v101, 0xffff0000, v68
	v_lshlrev_b32_e32 v102, 16, v69
	v_and_b32_e32 v103, 0xffff0000, v69
	v_pk_mul_f32 v[166:167], v[42:43], v[100:101]
	v_pk_mul_f32 v[168:169], v[44:45], v[102:103]
	v_lshlrev_b32_e32 v96, 16, v70
	v_and_b32_e32 v97, 0xffff0000, v70
	v_lshlrev_b32_e32 v98, 16, v71
	v_and_b32_e32 v99, 0xffff0000, v71
	v_pk_mul_f32 v[170:171], v[38:39], v[96:97]
	v_pk_mul_f32 v[172:173], v[40:41], v[98:99]
	v_lshlrev_b32_e32 v100, 16, v72
	v_and_b32_e32 v101, 0xffff0000, v72
	v_lshlrev_b32_e32 v102, 16, v73
	v_and_b32_e32 v103, 0xffff0000, v73
	v_pk_mul_f32 v[174:175], v[34:35], v[100:101]
	v_pk_mul_f32 v[176:177], v[36:37], v[102:103]
	v_lshlrev_b32_e32 v96, 16, v74
	v_and_b32_e32 v97, 0xffff0000, v74
	v_lshlrev_b32_e32 v98, 16, v75
	v_and_b32_e32 v99, 0xffff0000, v75
	v_pk_mul_f32 v[178:179], v[52:53], v[96:97]
	v_pk_mul_f32 v[180:181], v[54:55], v[98:99]
	v_lshlrev_b32_e32 v100, 16, v76
	v_and_b32_e32 v101, 0xffff0000, v76
	v_lshlrev_b32_e32 v102, 16, v77
	v_and_b32_e32 v103, 0xffff0000, v77
	v_pk_mul_f32 v[182:183], v[26:27], v[100:101]
	v_pk_mul_f32 v[184:185], v[28:29], v[102:103]
	v_lshlrev_b32_e32 v96, 16, v78
	v_and_b32_e32 v97, 0xffff0000, v78
	v_lshlrev_b32_e32 v98, 16, v79
	v_and_b32_e32 v99, 0xffff0000, v79
	v_pk_mul_f32 v[186:187], v[22:23], v[96:97]
	v_pk_mul_f32 v[188:189], v[24:25], v[98:99]
	v_lshlrev_b32_e32 v100, 16, v80
	v_and_b32_e32 v101, 0xffff0000, v80
	v_lshlrev_b32_e32 v102, 16, v81
	v_and_b32_e32 v103, 0xffff0000, v81
	v_pk_mul_f32 v[190:191], v[18:19], v[100:101]
	v_pk_mul_f32 v[192:193], v[20:21], v[102:103]
	v_lshlrev_b32_e32 v96, 16, v82
	v_and_b32_e32 v97, 0xffff0000, v82
	v_lshlrev_b32_e32 v98, 16, v83
	v_and_b32_e32 v99, 0xffff0000, v83
	v_pk_mul_f32 v[194:195], v[14:15], v[96:97]
	v_pk_mul_f32 v[196:197], v[16:17], v[98:99]
	v_lshlrev_b32_e32 v100, 16, v84
	v_and_b32_e32 v101, 0xffff0000, v84
	v_lshlrev_b32_e32 v102, 16, v85
	v_and_b32_e32 v103, 0xffff0000, v85
	v_pk_mul_f32 v[198:199], v[10:11], v[100:101]
	v_pk_mul_f32 v[200:201], v[12:13], v[102:103]
	v_lshlrev_b32_e32 v96, 16, v86
	v_and_b32_e32 v97, 0xffff0000, v86
	v_lshlrev_b32_e32 v98, 16, v87
	v_and_b32_e32 v99, 0xffff0000, v87
	v_pk_mul_f32 v[202:203], v[6:7], v[96:97]
	v_pk_mul_f32 v[204:205], v[8:9], v[98:99]
	v_lshlrev_b32_e32 v100, 16, v88
	v_and_b32_e32 v101, 0xffff0000, v88
	v_lshlrev_b32_e32 v102, 16, v89
	v_and_b32_e32 v103, 0xffff0000, v89
	v_pk_mul_f32 v[206:207], v[2:3], v[100:101]
	v_pk_mul_f32 v[208:209], v[4:5], v[102:103]
	s_lshl_b64 s[8:9], s[8:9], 1
	s_mov_b32 s14, 2
	v_mov_b32_e32 v18, v142
	v_readlane_b32 s12, v217, 30
	v_readlane_b32 s13, v217, 31
	s_add_u32 s12, s12, s8
	s_addc_u32 s13, s13, s9
	s_lshl_b64 s[8:9], s[10:11], 1
	s_add_u32 s8, s40, s8
	s_addc_u32 s9, s41, s9
	s_waitcnt lgkmcnt(0)
	v_lshlrev_b32_e32 v19, 4, v18
	v_bfe_i32 v2, v18, 27, 1
	v_lshrrev_b32_e32 v2, 22, v2
	v_add_u32_e32 v2, v19, v2
	v_and_b32_e32 v2, 0xfffffc00, v2
	v_ashrrev_i32_e32 v0, 31, v18
	v_sub_u32_e32 v2, v19, v2
	v_lshrrev_b32_e32 v0, 26, v0
	v_lshrrev_b32_e32 v3, 4, v2
	v_add_u32_e32 v0, v18, v0
	v_bitop3_b32 v3, v3, v2, 32 bitop3:0x6c
	v_ashrrev_i32_e32 v2, 31, v2
	v_ashrrev_i32_e32 v0, 6, v0
	v_lshrrev_b32_e32 v2, 26, v2
	v_lshlrev_b32_e32 v4, 3, v0
	v_add_u32_e32 v2, v3, v2
	v_and_b32_e32 v4, -16, v4
	v_ashrrev_i32_e32 v5, 6, v2
	v_add_u32_e32 v2, v5, v4
	v_mul_i32_i24_e32 v4, 64, v5
	v_lshlrev_b32_e32 v0, 5, v0
	v_sub_u32_e32 v3, v3, v4
	v_and_b32_e32 v0, 32, v0
	v_ashrrev_i16_sdwa v3, v146, sext(v3) dst_sel:DWORD dst_unused:UNUSED_PAD src0_sel:DWORD src1_sel:BYTE_0
	v_add_u32_sdwa v4, v0, sext(v3) dst_sel:DWORD dst_unused:UNUSED_PAD src0_sel:DWORD src1_sel:WORD_0
	v_ashrrev_i32_e32 v3, 31, v2
	v_lshlrev_b64 v[2:3], 11, v[2:3]
	v_ashrrev_i32_e32 v5, 31, v4
	v_lshl_add_u64 v[6:7], s[12:13], 0, v[2:3]
	v_lshlrev_b64 v[4:5], 1, v[4:5]
	v_add_u32_e32 v20, 0x2000, v19
	v_lshl_add_u64 v[14:15], v[6:7], 0, v[4:5]
	v_ashrrev_i32_e32 v6, 31, v20
	v_lshrrev_b32_e32 v6, 22, v6
	v_add_u32_e32 v6, v20, v6
	v_ashrrev_i32_e32 v7, 10, v6
	v_mul_i32_i24_e32 v6, 0x400, v7
	v_sub_u32_e32 v6, v20, v6
	v_lshrrev_b32_e32 v8, 4, v6
	v_bitop3_b32 v8, v8, v6, 32 bitop3:0x6c
	v_ashrrev_i32_e32 v9, 31, v8
	v_lshrrev_b32_e32 v9, 26, v9
	v_add_u32_e32 v9, v8, v9
	v_lshlrev_b32_e32 v6, 3, v7
	v_ashrrev_i32_e32 v10, 6, v9
	v_and_b32_e32 v9, 0xc0, v9
	v_and_b32_e32 v6, -16, v6
	v_lshlrev_b32_e32 v7, 5, v7
	v_sub_u32_e32 v8, v8, v9
	v_add_u32_e32 v6, v10, v6
	v_and_b32_e32 v7, 32, v7
	v_ashrrev_i16_sdwa v8, v146, sext(v8) dst_sel:DWORD dst_unused:UNUSED_PAD src0_sel:DWORD src1_sel:BYTE_0
	v_add_u32_sdwa v8, v7, sext(v8) dst_sel:DWORD dst_unused:UNUSED_PAD src0_sel:DWORD src1_sel:WORD_0
	v_ashrrev_i32_e32 v7, 31, v6
	v_lshlrev_b64 v[6:7], 11, v[6:7]
	v_ashrrev_i32_e32 v9, 31, v8
	v_add_u32_e32 v0, 0, v19
	v_lshl_add_u64 v[10:11], s[12:13], 0, v[6:7]
	v_lshlrev_b64 v[8:9], 1, v[8:9]
	v_readfirstlane_b32 s10, v0
	v_lshl_add_u64 v[22:23], v[10:11], 0, v[8:9]
	v_add_u32_e32 v10, 0x2000, v0
	v_add_u32_e32 v21, 0x4000, v19
	s_mov_b32 m0, s10
	v_readfirstlane_b32 s10, v10
	v_ashrrev_i32_e32 v10, 31, v21
	v_lshrrev_b32_e32 v10, 22, v10
	v_add_u32_e32 v10, v21, v10
	v_ashrrev_i32_e32 v11, 10, v10
	v_mul_i32_i24_e32 v10, 0x400, v11
	v_sub_u32_e32 v10, v21, v10
	v_lshrrev_b32_e32 v12, 4, v10
	v_bitop3_b32 v12, v12, v10, 32 bitop3:0x6c
	v_ashrrev_i32_e32 v13, 31, v12
	v_lshrrev_b32_e32 v13, 26, v13
	v_add_u32_e32 v13, v12, v13
	v_lshlrev_b32_e32 v10, 3, v11
	v_ashrrev_i32_e32 v16, 6, v13
	v_and_b32_e32 v13, 0xc0, v13
	v_and_b32_e32 v10, -16, v10
	v_lshlrev_b32_e32 v11, 5, v11
	v_sub_u32_e32 v12, v12, v13
	v_add_u32_e32 v10, v16, v10
	v_and_b32_e32 v11, 32, v11
	v_ashrrev_i16_sdwa v12, v146, sext(v12) dst_sel:DWORD dst_unused:UNUSED_PAD src0_sel:DWORD src1_sel:BYTE_0
	v_add_u32_sdwa v12, v11, sext(v12) dst_sel:DWORD dst_unused:UNUSED_PAD src0_sel:DWORD src1_sel:WORD_0
	v_ashrrev_i32_e32 v11, 31, v10
	v_lshlrev_b64 v[10:11], 11, v[10:11]
	v_ashrrev_i32_e32 v13, 31, v12
	v_lshl_add_u64 v[16:17], s[12:13], 0, v[10:11]
	v_lshlrev_b64 v[12:13], 1, v[12:13]
	v_lshl_add_u64 v[24:25], v[16:17], 0, v[12:13]
	v_add_u32_e32 v16, 0x4000, v0
	s_barrier
	global_load_lds_dwordx4 v[14:15], off
	s_mov_b32 m0, s10
	v_readfirstlane_b32 s10, v16
	v_lshl_add_u64 v[16:17], s[8:9], 0, v[2:3]
	v_lshl_add_u64 v[26:27], v[16:17], 0, v[4:5]
	v_add_u32_e32 v16, 0x8000, v0
	global_load_lds_dwordx4 v[22:23], off
	s_mov_b32 m0, s10
	v_readfirstlane_b32 s10, v16
	v_add_u32_e32 v28, 0xa000, v0
	global_load_lds_dwordx4 v[24:25], off
	s_mov_b32 m0, s10
	v_lshl_add_u64 v[16:17], s[8:9], 0, v[6:7]
	v_readfirstlane_b32 s8, v28
	v_add_u32_e32 v28, 0xc000, v0
	global_load_lds_dwordx4 v[26:27], off
	v_lshl_add_u64 v[16:17], v[16:17], 0, v[8:9]
	s_mov_b32 m0, s8
	v_readfirstlane_b32 s8, v28
	global_load_lds_dwordx4 v[16:17], off
	v_lshl_add_u64 v[14:15], v[14:15], 0, s[30:31]
	s_mov_b32 m0, s8
	v_add_u32_e32 v21, s18, v21
	global_load_lds_dwordx4 v[14:15], off
	v_lshl_add_u64 v[14:15], v[22:23], 0, s[30:31]
	v_add_u32_e32 v22, 0xe000, v0
	v_add_u32_e32 v19, s54, v19
	v_readfirstlane_b32 s8, v22
	s_mov_b32 m0, s8
	v_readfirstlane_b32 s8, v21
	global_load_lds_dwordx4 v[14:15], off
	v_lshl_add_u64 v[14:15], v[24:25], 0, s[30:31]
	s_mov_b32 m0, s8
	v_readfirstlane_b32 s8, v19
	global_load_lds_dwordx4 v[14:15], off
	v_lshl_add_u64 v[14:15], v[26:27], 0, s[30:31]
	s_mov_b32 m0, s8
	v_lshl_add_u64 v[10:11], s[4:5], 0, v[10:11]
	global_load_lds_dwordx4 v[14:15], off
	v_lshl_add_u64 v[14:15], v[16:17], 0, s[30:31]
	v_add_u32_e32 v16, s54, v20
	v_lshlrev_b32_e32 v17, 2, v18
	v_readfirstlane_b32 s8, v16
	s_mov_b32 m0, s8
	v_and_b32_e32 v16, 48, v18
	global_load_lds_dwordx4 v[14:15], off
	v_lshlrev_b32_e32 v15, 6, v18
	v_and_b32_e32 v15, 0x3c0, v15
	v_and_b32_e32 v17, 32, v17
	v_lshrrev_b32_e32 v14, 7, v18
	v_bitop3_b32 v15, v15, v17, v16 bitop3:0x36
	v_lshlrev_b32_e32 v16, 7, v18
	s_movk_i32 s8, 0x1800
	v_and_b32_e32 v16, 0x2000, v16
	v_mul_lo_u32 v14, v14, s8
	v_add3_u32 v81, v14, 0, v15
	v_add3_u32 v80, v16, s15, v15
	v_lshl_add_u64 v[14:15], s[6:7], 0, v[6:7]
	v_lshl_add_u64 v[14:15], v[14:15], 0, v[8:9]
	v_lshl_add_u64 v[70:71], s[2:3], 0, v[14:15]
	v_lshl_add_u64 v[14:15], s[6:7], 0, v[2:3]
	v_readlane_b32 s6, v214, 24
	v_lshl_add_u64 v[2:3], s[4:5], 0, v[2:3]
	v_readlane_b32 s7, v214, 25
	v_lshl_add_u64 v[6:7], s[4:5], 0, v[6:7]
	v_lshl_add_u64 v[2:3], v[2:3], 0, v[4:5]
	v_lshl_add_u64 v[14:15], v[14:15], 0, v[4:5]
	v_lshl_add_u64 v[10:11], v[10:11], 0, v[12:13]
	v_lshl_add_u64 v[6:7], v[6:7], 0, v[8:9]
	v_lshl_add_u64 v[78:79], s[6:7], 0, v[2:3]
	v_mov_b32_e32 v2, 0
	v_lshl_add_u64 v[72:73], s[2:3], 0, v[14:15]
	v_lshl_add_u64 v[74:75], s[6:7], 0, v[10:11]
	v_lshl_add_u64 v[76:77], s[6:7], 0, v[6:7]
	s_mov_b32 s6, 0
	s_mov_b64 s[4:5], 0
	v_mov_b32_e32 v3, v2
	v_mov_b32_e32 v4, v2
	v_mov_b32_e32 v5, v2
	v_mov_b32_e32 v6, v2
	v_mov_b32_e32 v7, v2
	v_mov_b32_e32 v8, v2
	v_mov_b32_e32 v9, v2
	v_mov_b32_e32 v10, v2
	v_mov_b32_e32 v11, v2
	v_mov_b32_e32 v12, v2
	v_mov_b32_e32 v13, v2
	v_mov_b32_e32 v14, v2
	v_mov_b32_e32 v15, v2
	v_mov_b32_e32 v16, v2
	v_mov_b32_e32 v17, v2
	v_mov_b32_e32 v18, v2
	v_mov_b32_e32 v19, v2
	v_mov_b32_e32 v20, v2
	v_mov_b32_e32 v21, v2
	v_mov_b32_e32 v22, v2
	v_mov_b32_e32 v23, v2
	v_mov_b32_e32 v24, v2
	v_mov_b32_e32 v25, v2
	v_mov_b32_e32 v26, v2
	v_mov_b32_e32 v27, v2
	v_mov_b32_e32 v28, v2
	v_mov_b32_e32 v29, v2
	v_mov_b32_e32 v30, v2
	v_mov_b32_e32 v31, v2
	v_mov_b32_e32 v32, v2
	v_mov_b32_e32 v33, v2
	v_mov_b32_e32 v34, v2
	v_mov_b32_e32 v35, v2
	v_mov_b32_e32 v36, v2
	v_mov_b32_e32 v37, v2
	v_mov_b32_e32 v38, v2
	v_mov_b32_e32 v39, v2
	v_mov_b32_e32 v40, v2
	v_mov_b32_e32 v41, v2
	v_mov_b32_e32 v42, v2
	v_mov_b32_e32 v43, v2
	v_mov_b32_e32 v44, v2
	v_mov_b32_e32 v45, v2
	v_mov_b32_e32 v46, v2
	v_mov_b32_e32 v47, v2
	v_mov_b32_e32 v48, v2
	v_mov_b32_e32 v49, v2
.LBB0_109:
	s_waitcnt vmcnt(5)
	s_barrier
	s_mul_i32 s7, s14, 0xc000
	v_add_u32_e32 v84, s7, v0
	v_add_u32_e32 v85, 0x2000, v84
	v_readfirstlane_b32 s7, v84
	v_lshl_add_u64 v[82:83], v[78:79], 0, s[4:5]
	s_mov_b32 m0, s7
	v_readfirstlane_b32 s7, v85
	v_add_u32_e32 v85, 0x4000, v84
	global_load_lds_dwordx4 v[82:83], off
	v_lshl_add_u64 v[82:83], v[76:77], 0, s[4:5]
	s_mov_b32 m0, s7
	v_readfirstlane_b32 s7, v85
	v_add_u32_e32 v85, 0x8000, v84
	global_load_lds_dwordx4 v[82:83], off
	v_lshl_add_u64 v[82:83], v[74:75], 0, s[4:5]
	s_mov_b32 m0, s7
	v_readfirstlane_b32 s7, v85
	v_add_u32_e32 v84, 0xa000, v84
	global_load_lds_dwordx4 v[82:83], off
	v_lshl_add_u64 v[82:83], v[72:73], 0, s[4:5]
	s_mov_b32 m0, s7
	v_readfirstlane_b32 s7, v84
	global_load_lds_dwordx4 v[82:83], off
	v_lshl_add_u64 v[82:83], v[70:71], 0, s[4:5]
	s_mov_b32 m0, s7
	s_mul_i32 s7, s6, 0xc000
	global_load_lds_dwordx4 v[82:83], off
	v_add_u32_e32 v118, s7, v81
	ds_read_b128 v[82:85], v118 offset:0
	ds_read_b128 v[86:89], v118 offset:2048
	ds_read_b128 v[90:93], v118 offset:4096
	v_add_u32_e32 v138, s7, v80
	ds_read_b128 v[94:97], v138 offset:0
	ds_read_b128 v[98:101], v138 offset:2048
	ds_read_b128 v[102:105], v138 offset:4096
	ds_read_b128 v[106:109], v138 offset:6144
	ds_read_b128 v[110:113], v118 offset:1024
	ds_read_b128 v[114:117], v118 offset:3072
	ds_read_b128 v[118:121], v118 offset:5120
	ds_read_b128 v[122:125], v138 offset:1024
	ds_read_b128 v[126:129], v138 offset:3072
	ds_read_b128 v[134:137], v138 offset:5120
	ds_read_b128 v[138:141], v138 offset:7168
	s_waitcnt lgkmcnt(7)
	s_nop 0
	v_mfma_f32_16x16x32_bf16 v[46:49], v[94:97], v[82:85], v[46:49]
	v_mfma_f32_16x16x32_bf16 v[42:45], v[98:101], v[82:85], v[42:45]
	v_mfma_f32_16x16x32_bf16 v[38:41], v[102:105], v[82:85], v[38:41]
	v_mfma_f32_16x16x32_bf16 v[34:37], v[106:109], v[82:85], v[34:37]
	v_mfma_f32_16x16x32_bf16 v[30:33], v[94:97], v[86:89], v[30:33]
	v_mfma_f32_16x16x32_bf16 v[26:29], v[98:101], v[86:89], v[26:29]
	v_mfma_f32_16x16x32_bf16 v[22:25], v[102:105], v[86:89], v[22:25]
	v_mfma_f32_16x16x32_bf16 v[18:21], v[106:109], v[86:89], v[18:21]
	v_mfma_f32_16x16x32_bf16 v[14:17], v[94:97], v[90:93], v[14:17]
	v_mfma_f32_16x16x32_bf16 v[10:13], v[98:101], v[90:93], v[10:13]
	v_mfma_f32_16x16x32_bf16 v[6:9], v[102:105], v[90:93], v[6:9]
	v_mfma_f32_16x16x32_bf16 v[2:5], v[106:109], v[90:93], v[2:5]
	s_waitcnt lgkmcnt(0)
	v_mfma_f32_16x16x32_bf16 v[46:49], v[122:125], v[110:113], v[46:49]
	v_mfma_f32_16x16x32_bf16 v[42:45], v[126:129], v[110:113], v[42:45]
	v_mfma_f32_16x16x32_bf16 v[38:41], v[134:137], v[110:113], v[38:41]
	v_mfma_f32_16x16x32_bf16 v[34:37], v[138:141], v[110:113], v[34:37]
	v_mfma_f32_16x16x32_bf16 v[30:33], v[122:125], v[114:117], v[30:33]
	v_mfma_f32_16x16x32_bf16 v[26:29], v[126:129], v[114:117], v[26:29]
	v_mfma_f32_16x16x32_bf16 v[22:25], v[134:137], v[114:117], v[22:25]
	v_mfma_f32_16x16x32_bf16 v[18:21], v[138:141], v[114:117], v[18:21]
	v_mfma_f32_16x16x32_bf16 v[14:17], v[122:125], v[118:121], v[14:17]
	v_mfma_f32_16x16x32_bf16 v[10:13], v[126:129], v[118:121], v[10:13]
	v_mfma_f32_16x16x32_bf16 v[6:9], v[134:137], v[118:121], v[6:9]
	v_mfma_f32_16x16x32_bf16 v[2:5], v[138:141], v[118:121], v[2:5]
	s_add_i32 s7, s6, 1
	s_cmp_lg_u32 s6, 2
	s_cselect_b32 s6, s7, 0
	s_add_i32 s7, s14, 1
	s_cmp_lg_u32 s14, 2
	s_cselect_b32 s14, s7, 0
	s_add_u32 s4, s4, 0x80
	s_addc_u32 s5, s5, 0
	s_cmpk_lg_i32 s4, 0x700
	s_cbranch_scc1 .LBB0_109
	s_waitcnt vmcnt(5)
	s_barrier
	v_add_u32_e32 v0, 0x18000, v81
	ds_read_b128 v[70:73], v0 offset:0
	ds_read_b128 v[74:77], v0 offset:2048
	ds_read_b128 v[82:85], v0 offset:4096
	v_add_u32_e32 v78, 0x18000, v80
	ds_read_b128 v[86:89], v78 offset:0
	ds_read_b128 v[90:93], v78 offset:2048
	ds_read_b128 v[94:97], v78 offset:4096
	ds_read_b128 v[98:101], v78 offset:6144
	ds_read_b128 v[102:105], v0 offset:1024
	ds_read_b128 v[106:109], v0 offset:3072
	ds_read_b128 v[110:113], v0 offset:5120
	ds_read_b128 v[114:117], v78 offset:1024
	ds_read_b128 v[118:121], v78 offset:3072
	ds_read_b128 v[122:125], v78 offset:5120
	ds_read_b128 v[126:129], v78 offset:7168
	s_waitcnt lgkmcnt(7)
	s_nop 0
	v_mfma_f32_16x16x32_bf16 v[46:49], v[86:89], v[70:73], v[46:49]
	v_mfma_f32_16x16x32_bf16 v[42:45], v[90:93], v[70:73], v[42:45]
	v_mfma_f32_16x16x32_bf16 v[38:41], v[94:97], v[70:73], v[38:41]
	v_mfma_f32_16x16x32_bf16 v[34:37], v[98:101], v[70:73], v[34:37]
	v_mfma_f32_16x16x32_bf16 v[30:33], v[86:89], v[74:77], v[30:33]
	v_mfma_f32_16x16x32_bf16 v[26:29], v[90:93], v[74:77], v[26:29]
	v_mfma_f32_16x16x32_bf16 v[22:25], v[94:97], v[74:77], v[22:25]
	v_mfma_f32_16x16x32_bf16 v[18:21], v[98:101], v[74:77], v[18:21]
	v_mfma_f32_16x16x32_bf16 v[14:17], v[86:89], v[82:85], v[14:17]
	v_mfma_f32_16x16x32_bf16 v[10:13], v[90:93], v[82:85], v[10:13]
	v_mfma_f32_16x16x32_bf16 v[6:9], v[94:97], v[82:85], v[6:9]
	v_mfma_f32_16x16x32_bf16 v[2:5], v[98:101], v[82:85], v[2:5]
	s_waitcnt lgkmcnt(0)
	v_mfma_f32_16x16x32_bf16 v[46:49], v[114:117], v[102:105], v[46:49]
	v_mfma_f32_16x16x32_bf16 v[42:45], v[118:121], v[102:105], v[42:45]
	v_mfma_f32_16x16x32_bf16 v[38:41], v[122:125], v[102:105], v[38:41]
	v_mfma_f32_16x16x32_bf16 v[34:37], v[126:129], v[102:105], v[34:37]
	v_mfma_f32_16x16x32_bf16 v[30:33], v[114:117], v[106:109], v[30:33]
	v_mfma_f32_16x16x32_bf16 v[26:29], v[118:121], v[106:109], v[26:29]
	v_mfma_f32_16x16x32_bf16 v[22:25], v[122:125], v[106:109], v[22:25]
	v_mfma_f32_16x16x32_bf16 v[18:21], v[126:129], v[106:109], v[18:21]
	v_mfma_f32_16x16x32_bf16 v[14:17], v[114:117], v[110:113], v[14:17]
	v_mfma_f32_16x16x32_bf16 v[10:13], v[118:121], v[110:113], v[10:13]
	v_mfma_f32_16x16x32_bf16 v[6:9], v[122:125], v[110:113], v[6:9]
	v_mfma_f32_16x16x32_bf16 v[2:5], v[126:129], v[110:113], v[2:5]
	s_waitcnt vmcnt(0)
	s_barrier
	ds_read_b128 v[70:73], v81 offset:0
	ds_read_b128 v[74:77], v81 offset:2048
	ds_read_b128 v[82:85], v81 offset:4096
	ds_read_b128 v[86:89], v80 offset:0
	ds_read_b128 v[90:93], v80 offset:2048
	ds_read_b128 v[94:97], v80 offset:4096
	ds_read_b128 v[98:101], v80 offset:6144
	ds_read_b128 v[102:105], v81 offset:1024
	ds_read_b128 v[106:109], v81 offset:3072
	ds_read_b128 v[110:113], v81 offset:5120
	ds_read_b128 v[114:117], v80 offset:1024
	ds_read_b128 v[118:121], v80 offset:3072
	ds_read_b128 v[122:125], v80 offset:5120
	ds_read_b128 v[78:81], v80 offset:7168
	s_waitcnt lgkmcnt(7)
	s_nop 0
	v_mfma_f32_16x16x32_bf16 v[46:49], v[86:89], v[70:73], v[46:49]
	v_mfma_f32_16x16x32_bf16 v[42:45], v[90:93], v[70:73], v[42:45]
	v_mfma_f32_16x16x32_bf16 v[38:41], v[94:97], v[70:73], v[38:41]
	v_mfma_f32_16x16x32_bf16 v[34:37], v[98:101], v[70:73], v[34:37]
	v_mfma_f32_16x16x32_bf16 v[30:33], v[86:89], v[74:77], v[30:33]
	v_mfma_f32_16x16x32_bf16 v[26:29], v[90:93], v[74:77], v[26:29]
	v_mfma_f32_16x16x32_bf16 v[22:25], v[94:97], v[74:77], v[22:25]
	v_mfma_f32_16x16x32_bf16 v[18:21], v[98:101], v[74:77], v[18:21]
	v_mfma_f32_16x16x32_bf16 v[14:17], v[86:89], v[82:85], v[14:17]
	v_mfma_f32_16x16x32_bf16 v[10:13], v[90:93], v[82:85], v[10:13]
	v_mfma_f32_16x16x32_bf16 v[6:9], v[94:97], v[82:85], v[6:9]
	v_mfma_f32_16x16x32_bf16 v[2:5], v[98:101], v[82:85], v[2:5]
	s_waitcnt lgkmcnt(0)
	v_mfma_f32_16x16x32_bf16 v[46:49], v[114:117], v[102:105], v[46:49]
	v_mfma_f32_16x16x32_bf16 v[42:45], v[118:121], v[102:105], v[42:45]
	v_mfma_f32_16x16x32_bf16 v[70:73], v[122:125], v[102:105], v[38:41]
	v_mfma_f32_16x16x32_bf16 v[34:37], v[78:81], v[102:105], v[34:37]
	v_mfma_f32_16x16x32_bf16 v[30:33], v[114:117], v[106:109], v[30:33]
	v_mfma_f32_16x16x32_bf16 v[26:29], v[118:121], v[106:109], v[26:29]
	v_mfma_f32_16x16x32_bf16 v[22:25], v[122:125], v[106:109], v[22:25]
	v_mfma_f32_16x16x32_bf16 v[18:21], v[78:81], v[106:109], v[18:21]
	v_mfma_f32_16x16x32_bf16 v[14:17], v[114:117], v[110:113], v[14:17]
	v_mfma_f32_16x16x32_bf16 v[10:13], v[118:121], v[110:113], v[10:13]
	v_mfma_f32_16x16x32_bf16 v[6:9], v[122:125], v[110:113], v[6:9]
	v_mfma_f32_16x16x32_bf16 v[2:5], v[78:81], v[110:113], v[2:5]
	s_nop 7
	s_nop 1
	s_and_b32 vcc_lo, s42, 31
	s_mul_i32 vcc_lo, vcc_lo, 192
	s_lshr_b32 vcc_hi, s42, 5
	s_lshl_b32 vcc_hi, vcc_hi, 8
	v_and_b32_e32 v93, 15, v142
	v_lshrrev_b32_e32 v94, 7, v142
	v_mad_u32_u24 v93, v94, 48, v93
	v_add_u32_e32 v93, vcc_lo, v93
	v_lshrrev_b32_e32 v94, 4, v142
	v_and_b32_e32 v94, 3, v94
	v_lshlrev_b32_e32 v94, 3, v94
	v_lshrrev_b32_e32 v95, 6, v142
	v_and_b32_e32 v95, 1, v95
	v_lshl_add_u32 v94, v95, 7, v94
	v_add_u32_e32 v94, vcc_hi, v94
	v_lshl_add_u32 v90, v93, 11, v94
	v_add_u32_e32 v91, 0x8000, v90
	v_add_u32_e32 v92, 0x8000, v91
	s_waitcnt vmcnt(0)
	v_lshlrev_b32_e32 v96, 16, v218
	v_and_b32_e32 v97, 0xffff0000, v218
	v_lshlrev_b32_e32 v98, 16, v219
	v_and_b32_e32 v99, 0xffff0000, v219
	v_pk_fma_f32 v[162:163], v[46:47], v[96:97], v[162:163]
	v_pk_fma_f32 v[164:165], v[48:49], v[98:99], v[164:165]
	s_nop 0
	v_cvt_pk_bf16_f32 v104, v162, v163
	v_cvt_pk_bf16_f32 v105, v164, v165
	global_store_dwordx2 v90, v[104:105], s[22:23] offset:0
	v_lshlrev_b32_e32 v100, 16, v220
	v_and_b32_e32 v101, 0xffff0000, v220
	v_lshlrev_b32_e32 v102, 16, v221
	v_and_b32_e32 v103, 0xffff0000, v221
	v_pk_fma_f32 v[166:167], v[42:43], v[100:101], v[166:167]
	v_pk_fma_f32 v[168:169], v[44:45], v[102:103], v[168:169]
	s_nop 0
	v_cvt_pk_bf16_f32 v106, v166, v167
	v_cvt_pk_bf16_f32 v107, v168, v169
	global_store_dwordx2 v90, v[106:107], s[22:23] offset:32
	v_lshlrev_b32_e32 v96, 16, v222
	v_and_b32_e32 v97, 0xffff0000, v222
	v_lshlrev_b32_e32 v98, 16, v223
	v_and_b32_e32 v99, 0xffff0000, v223
	v_pk_fma_f32 v[170:171], v[70:71], v[96:97], v[170:171]
	v_pk_fma_f32 v[172:173], v[72:73], v[98:99], v[172:173]
	s_nop 0
	v_cvt_pk_bf16_f32 v104, v170, v171
	v_cvt_pk_bf16_f32 v105, v172, v173
	global_store_dwordx2 v90, v[104:105], s[22:23] offset:64
	v_lshlrev_b32_e32 v100, 16, v224
	v_and_b32_e32 v101, 0xffff0000, v224
	v_lshlrev_b32_e32 v102, 16, v225
	v_and_b32_e32 v103, 0xffff0000, v225
	v_pk_fma_f32 v[174:175], v[34:35], v[100:101], v[174:175]
	v_pk_fma_f32 v[176:177], v[36:37], v[102:103], v[176:177]
	s_nop 0
	v_cvt_pk_bf16_f32 v106, v174, v175
	v_cvt_pk_bf16_f32 v107, v176, v177
	global_store_dwordx2 v90, v[106:107], s[22:23] offset:96
	v_lshlrev_b32_e32 v96, 16, v226
	v_and_b32_e32 v97, 0xffff0000, v226
	v_lshlrev_b32_e32 v98, 16, v227
	v_and_b32_e32 v99, 0xffff0000, v227
	v_pk_fma_f32 v[178:179], v[30:31], v[96:97], v[178:179]
	v_pk_fma_f32 v[180:181], v[32:33], v[98:99], v[180:181]
	s_nop 0
	v_cvt_pk_bf16_f32 v104, v178, v179
	v_cvt_pk_bf16_f32 v105, v180, v181
	global_store_dwordx2 v91, v[104:105], s[22:23] offset:0
	v_lshlrev_b32_e32 v100, 16, v228
	v_and_b32_e32 v101, 0xffff0000, v228
	v_lshlrev_b32_e32 v102, 16, v229
	v_and_b32_e32 v103, 0xffff0000, v229
	v_pk_fma_f32 v[182:183], v[26:27], v[100:101], v[182:183]
	v_pk_fma_f32 v[184:185], v[28:29], v[102:103], v[184:185]
	s_nop 0
	v_cvt_pk_bf16_f32 v106, v182, v183
	v_cvt_pk_bf16_f32 v107, v184, v185
	global_store_dwordx2 v91, v[106:107], s[22:23] offset:32
	v_lshlrev_b32_e32 v96, 16, v230
	v_and_b32_e32 v97, 0xffff0000, v230
	v_lshlrev_b32_e32 v98, 16, v231
	v_and_b32_e32 v99, 0xffff0000, v231
	v_pk_fma_f32 v[186:187], v[22:23], v[96:97], v[186:187]
	v_pk_fma_f32 v[188:189], v[24:25], v[98:99], v[188:189]
	s_nop 0
	v_cvt_pk_bf16_f32 v104, v186, v187
	v_cvt_pk_bf16_f32 v105, v188, v189
	global_store_dwordx2 v91, v[104:105], s[22:23] offset:64
	v_lshlrev_b32_e32 v100, 16, v232
	v_and_b32_e32 v101, 0xffff0000, v232
	v_lshlrev_b32_e32 v102, 16, v233
	v_and_b32_e32 v103, 0xffff0000, v233
	v_pk_fma_f32 v[190:191], v[18:19], v[100:101], v[190:191]
	v_pk_fma_f32 v[192:193], v[20:21], v[102:103], v[192:193]
	s_nop 0
	v_cvt_pk_bf16_f32 v106, v190, v191
	v_cvt_pk_bf16_f32 v107, v192, v193
	global_store_dwordx2 v91, v[106:107], s[22:23] offset:96
	v_lshlrev_b32_e32 v96, 16, v234
	v_and_b32_e32 v97, 0xffff0000, v234
	v_lshlrev_b32_e32 v98, 16, v235
	v_and_b32_e32 v99, 0xffff0000, v235
	v_pk_fma_f32 v[194:195], v[14:15], v[96:97], v[194:195]
	v_pk_fma_f32 v[196:197], v[16:17], v[98:99], v[196:197]
	s_nop 0
	v_cvt_pk_bf16_f32 v104, v194, v195
	v_cvt_pk_bf16_f32 v105, v196, v197
	global_store_dwordx2 v92, v[104:105], s[22:23] offset:0
	v_lshlrev_b32_e32 v100, 16, v236
	v_and_b32_e32 v101, 0xffff0000, v236
	v_lshlrev_b32_e32 v102, 16, v237
	v_and_b32_e32 v103, 0xffff0000, v237
	v_pk_fma_f32 v[198:199], v[10:11], v[100:101], v[198:199]
	v_pk_fma_f32 v[200:201], v[12:13], v[102:103], v[200:201]
	s_nop 0
	v_cvt_pk_bf16_f32 v106, v198, v199
	v_cvt_pk_bf16_f32 v107, v200, v201
	global_store_dwordx2 v92, v[106:107], s[22:23] offset:32
	v_lshlrev_b32_e32 v96, 16, v238
	v_and_b32_e32 v97, 0xffff0000, v238
	v_lshlrev_b32_e32 v98, 16, v239
	v_and_b32_e32 v99, 0xffff0000, v239
	v_pk_fma_f32 v[202:203], v[6:7], v[96:97], v[202:203]
	v_pk_fma_f32 v[204:205], v[8:9], v[98:99], v[204:205]
	s_nop 0
	v_cvt_pk_bf16_f32 v104, v202, v203
	v_cvt_pk_bf16_f32 v105, v204, v205
	global_store_dwordx2 v92, v[104:105], s[22:23] offset:64
	v_lshlrev_b32_e32 v100, 16, v240
	v_and_b32_e32 v101, 0xffff0000, v240
	v_lshlrev_b32_e32 v102, 16, v241
	v_and_b32_e32 v103, 0xffff0000, v241
	v_pk_fma_f32 v[206:207], v[2:3], v[100:101], v[206:207]
	v_pk_fma_f32 v[208:209], v[4:5], v[102:103], v[208:209]
	s_nop 0
	v_cvt_pk_bf16_f32 v106, v206, v207
	v_cvt_pk_bf16_f32 v107, v208, v209
	global_store_dwordx2 v92, v[106:107], s[22:23] offset:96
	s_add_i32 s42, s42, s84
	s_cmpk_gt_i32 s42, 0xff
	s_cbranch_scc0 .LBB0_106
